# stack v71 + next-item prefetch in the s=2 item loop: the z rows of the workgroup's next gmlp item are touched (one dword per 128-byte line) one item ahead
# baseline (speedup 1.0000x reference)
; __device__ __forceinline__ void lds_barrier() { asm volatile("s_waitcnt lgkmcnt(0)" ::: "memory"); __builtin_amdgcn_s_barrier(); asm volatile("" ::: "memory"); }
; __device__ __forceinline__ int opaque_bid() { int t = blockIdx.x; asm volatile("" : "+s"(t)); return t; }
; __device__ __forceinline__ int opaque_gd() { int t = gridDim.x; asm volatile("" : "+s"(t)); return t; }
; __device__ __forceinline__ Params fetchP(const LAS Params* lp0) { unsigned la = (unsigned)(unsigned long long)lp0; asm volatile("" : "+v"(la)); const LAS Params* lp = (const LAS Params*)la; Params q; PFIELDS(PFETCH) q.ph_lo = 0; q.ph_hi = 0; return q; }
; __device__ __forceinline__ void gmlp_item(const Params& p, int l, int item, LAS unsigned char* lds) {
;     ...
;     const size_t T0 = (size_t)b * SEQ + blk * 128;
;     lds_barrier();
;     const int nks = (wid >> 1) + 1;
;     const size_t Tw = T0 + wid * 16 + fr;
;     bf16x8 bwp[4]; u32x2 uwp[4];
;     { const bf16_t* wp = p.gmw + (((size_t)l * 4 + g) * 128 + wid * 16 + fr) * 128 + fq * 8;
; #pragma unroll
;       for (int ks = 0; ks < 4; ++ks) bwp[ks] = *(const bf16x8*)(wp + (ks < nks ? ks : 0) * 32);
; #pragma unroll
;       for (int ct = 0; ct < 4; ++ct) uwp[ct] = *(const u32x2*)(p.z + Tw * ZLD + 1792 + g * 64 + ct * 16 + fq * 4); }
;     const float bsv = p.gm_bs[((size_t)l * 4 + g) * 128 + wid * 16 + fr];
;     { const int pp = tid >> 2, qd = tid & 3; const bf16_t* vp = p.z + (T0 + pp) * ZLD + 2048 + qd * 16;
; __device__ __forceinline__ void run_phase(const LAS Params* lp, int ph, LAS unsigned char* lds) {
;     ...
;     case 2: for (int it = opaque_bid(); it < 1280; it += opaque_gd()) { const Params p = fetchP(lp); const int jx = (it & ~255) + (it & 7) * 32 + ((it & 255) >> 3);
;             if (it < 256) hgrn_item(p, l, jx, 1, lds); else if (it < 768) gmlp_item(p, l, jx - 256, lds); else lru_fix_item(p, l, jx - 768); } break;
.LBB0_307:
	v_mov_b32_e32 v0, s84
	ds_read2_b64 v[12:15], v0 offset0:8 offset1:9
	ds_read2_b64 v[8:11], v0 offset0:29 offset1:30
	ds_read2_b64 v[16:19], v0 offset0:11 offset1:31
	ds_read2_b64 v[20:23], v0 offset0:33 offset1:37
	ds_read2_b64 v[4:7], v0 offset0:39 offset1:40
	ds_read_b64 v[0:1], v0 offset:328
	s_lshl_b32 s7, s72, 5
	s_and_b32 s6, s72, 0xffffff00
	s_and_b32 s7, s7, 0xe0
	s_or_b32 s21, s7, s6
	s_mov_b64 s[6:7], -1
	s_cmpk_gt_i32 s72, 0xff
	s_waitcnt lgkmcnt(0)
	v_readfirstlane_b32 s2, v12
	v_readfirstlane_b32 s20, v13
	v_readfirstlane_b32 s23, v14
	v_readfirstlane_b32 s36, v15
	v_readfirstlane_b32 s34, v8
	v_readfirstlane_b32 s35, v9
	v_readfirstlane_b32 s9, v10
	v_readfirstlane_b32 s0, v16
	v_readfirstlane_b32 s14, v17
	v_readfirstlane_b32 s30, v18
	v_readfirstlane_b32 s31, v19
	v_readfirstlane_b32 s33, v11
	v_readfirstlane_b32 s4, v20
	v_readfirstlane_b32 s5, v21
	v_readfirstlane_b32 s18, v22
	v_readfirstlane_b32 s19, v23
	v_readfirstlane_b32 s15, v4
	v_readfirstlane_b32 s17, v5
	v_readfirstlane_b32 s10, v6
	v_readfirstlane_b32 s11, v7
	v_readfirstlane_b32 s12, v0
	v_readfirstlane_b32 s13, v1
	s_cmp_lt_u32 s72, 0x200
	s_cbranch_scc0 .Lpf2_skip
	s_bfe_u32 s98, s72, 0x50003
	s_or_b32 s98, s21, s98
	s_lshr_b32 s99, s98, 6
	s_lshl_b32 s99, s99, 11
	s_bfe_u32 s98, s98, 0x40002
	s_lshl_b32 s98, s98, 7
	s_or_b32 s99, s99, s98
	v_lshrrev_b32_e32 v127, 2, v202
	v_add_u32_e32 v127, s99, v127
	v_mul_u32_u24_e32 v127, 0x1600, v127
	v_and_b32_e32 v128, 3, v202
	v_lshlrev_b32_e32 v128, 7, v128
	v_add_u32_e32 v127, v127, v128
	v_add_u32_e32 v127, 0x1000, v127
	global_load_dword v126, v127, s[34:35]
	global_load_dword v126, v127, s[34:35] offset:-512
; __device__ __forceinline__ int opaque_tid() { int t = threadIdx.x; asm volatile("" : "+v"(t)); return t; }
; __device__ __forceinline__ void lru_fix_item(const Params& p, int l, int item) {
;     const int tid = opaque_tid(), wid = tid >> 6, lane = tid & 63;
;     const int b = item >> 6, h = (item >> 4) & 3, seg = item & 15;
;     const int t0 = seg * 128 + wid * 16; const size_t Tb = (size_t)b * SEQ;
;     const int ch = h * 64 + lane;
;     const float* sc = (const float*)p.hbuf + ((((size_t)b * 4 + h) * 16 + seg) * 8 + wid) * 2048 + lane * 16;
;     f32x4 hv[4], av[4]; unsigned gr[16];
; #pragma unroll
;     for (int q = 0; q < 4; ++q) { hv[q] = *(const f32x4*)(sc + q * 4); av[q] = *(const f32x4*)(sc + 1024 + q * 4); }
; #pragma unroll
;     for (int i = 0; i < 16; ++i) gr[i] = p.z[(Tb + t0 + i) * ZLD + 2560 + ch];
;     const float* car = p.lru_carry + (((size_t)b * 4 + h) * 16) * 128;
;     float Hin = 0.f;
; #pragma unroll 4
;     for (int s = 0; s < seg; ++s) { const float as = car[s * 128 + lane * 2], hs = car[s * 128 + lane * 2 + 1]; Hin = as * Hin + hs; }
.Lpf2_skip:
	s_cmpk_gt_i32 s72, 0xff
	s_cbranch_scc0 .LBB0_326
	s_bfe_u32 s6, s72, 0x50003
	s_or_b32 s16, s21, s6
	s_cmpk_gt_u32 s72, 0x2ff
	s_mov_b64 s[6:7], -1
	s_cbranch_scc0 .LBB0_319
	s_add_i32 s6, s21, 0xfffffd00
	s_ashr_i32 s38, s6, 6
	s_bfe_u32 s37, s16, 0x20004
	s_ashr_i32 s39, s38, 31
	s_lshl_b64 s[6:7], s[38:39], 6
	s_lshl_b32 s8, s37, 4
	s_bfe_u32 s22, s72, 0x40003
	s_or_b32 s8, s6, s8
	s_or_b32 s6, s8, s22
	v_mov_b32_e32 v1, v202
	s_lshl_b64 s[40:41], s[6:7], 16
	s_add_u32 s40, s9, s40
	v_ashrrev_i32_e32 v0, 6, v1
	v_and_b32_e32 v36, 63, v1
	v_ashrrev_i32_e32 v1, 31, v0
	s_addc_u32 s41, s33, s41
	s_lshl_b32 s6, s22, 7
	v_lshlrev_b64 v[4:5], 13, v[0:1]
	v_lshl_add_u32 v0, v0, 4, s6
	s_lshl_b64 s[38:39], s[38:39], 11
	v_ashrrev_i32_e32 v1, 31, v0
	v_lshl_add_u64 v[4:5], s[40:41], 0, v[4:5]
	v_lshlrev_b32_e32 v6, 6, v36
	v_mov_b32_e32 v7, v2
	v_lshl_add_u64 v[38:39], s[38:39], 0, v[0:1]
	v_mov_b64_e32 v[0:1], s[34:35]
	s_movk_i32 s6, 0x1600
	v_lshl_add_u64 v[8:9], v[4:5], 0, v[6:7]
	s_mov_b64 s[40:41], 0x1000
	v_lshl_or_b32 v3, s37, 6, v36
	v_mad_u64_u32 v[40:41], s[38:39], v38, s6, v[0:1]
	v_lshl_add_u64 v[24:25], v[8:9], 0, s[40:41]
	global_load_dwordx4 v[4:7], v[8:9], off offset:48
	global_load_dwordx4 v[12:15], v[8:9], off offset:32
	global_load_dwordx4 v[20:23], v[8:9], off offset:16
	global_load_dwordx4 v[28:31], v[8:9], off
	v_add_co_u32_e32 v8, vcc, s80, v8
	v_mad_i32_i24 v41, v39, s6, v41
	v_lshlrev_b32_e32 v0, 1, v3
	v_mov_b32_e32 v1, v2
	v_addc_co_u32_e32 v9, vcc, 0, v9, vcc
	v_lshl_add_u64 v[40:41], v[40:41], 0, v[0:1]
	v_add_co_u32_e32 v42, vcc, s80, v40
	global_load_dwordx4 v[32:35], v[8:9], off
	s_nop 0
	global_load_dwordx4 v[8:11], v[24:25], off offset:48
	global_load_dwordx4 v[16:19], v[24:25], off offset:32
	s_nop 0
	global_load_dwordx4 v[24:27], v[24:25], off offset:16
	v_addc_co_u32_e32 v43, vcc, 0, v41, vcc
	global_load_ushort v1, v[42:43], off offset:1024
	v_add_co_u32_e32 v42, vcc, s81, v40
	s_movk_i32 s6, 0x4000
	s_nop 0
	v_addc_co_u32_e32 v43, vcc, 0, v41, vcc
	global_load_ushort v55, v[42:43], off offset:2560
	v_add_co_u32_e32 v42, vcc, s6, v40
	s_movk_i32 s6, 0x5000
	s_nop 0
	v_addc_co_u32_e32 v43, vcc, 0, v41, vcc
	global_load_ushort v54, v[42:43], off
	v_add_co_u32_e32 v42, vcc, s6, v40
	s_movk_i32 s6, 0x6000
	s_nop 0
	v_addc_co_u32_e32 v43, vcc, 0, v41, vcc
	global_load_ushort v53, v[42:43], off offset:1536
	v_add_co_u32_e32 v42, vcc, s6, v40
	s_mov_b32 s6, 0x8000
	s_nop 0
	v_addc_co_u32_e32 v43, vcc, 0, v41, vcc
	global_load_ushort v52, v[42:43], off offset:3072
	v_add_co_u32_e32 v42, vcc, s6, v40
	s_mov_b32 s6, 0x9000
	s_nop 0
	v_addc_co_u32_e32 v43, vcc, 0, v41, vcc
	global_load_ushort v51, v[42:43], off offset:512
	v_add_co_u32_e32 v42, vcc, s6, v40
	s_mov_b32 s6, 0xa000
	s_nop 0
	v_addc_co_u32_e32 v43, vcc, 0, v41, vcc
	global_load_ushort v50, v[42:43], off offset:2048
	v_add_co_u32_e32 v42, vcc, s6, v40
	s_mov_b32 s6, 0xc000
	s_nop 0
	v_addc_co_u32_e32 v43, vcc, 0, v41, vcc
	global_load_ushort v49, v[42:43], off offset:3584
	v_add_co_u32_e32 v42, vcc, s6, v40
	s_mov_b32 s6, 0xd000
	s_nop 0
	v_addc_co_u32_e32 v43, vcc, 0, v41, vcc
	global_load_ushort v48, v[42:43], off offset:1024
	v_add_co_u32_e32 v42, vcc, s6, v40
	s_mov_b32 s6, 0xf000
	s_nop 0
	v_addc_co_u32_e32 v43, vcc, 0, v41, vcc
	global_load_ushort v47, v[42:43], off offset:2560
	v_add_co_u32_e32 v42, vcc, s6, v40
	s_mov_b32 s6, 0x10000
	s_nop 0
	v_addc_co_u32_e32 v43, vcc, 0, v41, vcc
	global_load_ushort v46, v[42:43], off
	v_add_co_u32_e32 v42, vcc, s6, v40
	s_cmp_eq_u32 s22, 0
	s_nop 0
	v_addc_co_u32_e32 v43, vcc, 0, v41, vcc
	global_load_ushort v45, v[42:43], off offset:1536
	v_add_co_u32_e32 v42, vcc, 0x11000, v40
	s_nop 1
	v_addc_co_u32_e32 v43, vcc, 0, v41, vcc
	global_load_ushort v44, v[42:43], off offset:3072
	v_add_co_u32_e32 v42, vcc, 0x13000, v40
	s_nop 1
	v_addc_co_u32_e32 v43, vcc, 0, v41, vcc
	v_add_co_u32_e32 v56, vcc, 0x14000, v40
	global_load_ushort v43, v[42:43], off offset:512
	s_nop 0
	v_addc_co_u32_e32 v57, vcc, 0, v41, vcc
	v_add_co_u32_e32 v40, vcc, 0x15000, v40
	global_load_ushort v42, v[56:57], off offset:2048
	s_nop 0
	v_addc_co_u32_e32 v41, vcc, 0, v41, vcc
	global_load_ushort v3, v[40:41], off offset:3584
	s_cbranch_scc1 .LBB0_314
	s_mov_b32 s9, s7
	s_lshl_b64 s[6:7], s[8:9], 9
	s_add_u32 s6, s15, s6
	s_addc_u32 s7, s17, s7
	v_lshlrev_b32_e32 v56, 3, v36
	s_mov_b32 s38, 0x16000
	s_add_u32 s8, s6, 0x1000
	s_addc_u32 s9, s7, 0
	s_cmp_le_u32 s22, 0
	s_cbranch_scc1 .Llrufix_issued
	global_load_dwordx2 v[62:63], v56, s[6:7] offset:0
	s_cmp_le_u32 s22, 1
	s_cbranch_scc1 .Llrufix_issued
	global_load_dwordx2 v[64:65], v56, s[6:7] offset:512
	s_cmp_le_u32 s22, 2
	s_cbranch_scc1 .Llrufix_issued
	global_load_dwordx2 v[66:67], v56, s[6:7] offset:1024
	s_cmp_le_u32 s22, 3
	s_cbranch_scc1 .Llrufix_issued
	global_load_dwordx2 v[68:69], v56, s[6:7] offset:1536
	s_cmp_le_u32 s22, 4
	s_cbranch_scc1 .Llrufix_issued
	global_load_dwordx2 v[70:71], v56, s[6:7] offset:2048
	s_cmp_le_u32 s22, 5
	s_cbranch_scc1 .Llrufix_issued
	global_load_dwordx2 v[72:73], v56, s[6:7] offset:2560
	s_cmp_le_u32 s22, 6
	s_cbranch_scc1 .Llrufix_issued
	global_load_dwordx2 v[74:75], v56, s[6:7] offset:3072
	s_cmp_le_u32 s22, 7
	s_cbranch_scc1 .Llrufix_issued
	global_load_dwordx2 v[76:77], v56, s[6:7] offset:3584
	s_cmp_le_u32 s22, 8
	s_cbranch_scc1 .Llrufix_issued
	global_load_dwordx2 v[78:79], v56, s[8:9] offset:0
	s_cmp_le_u32 s22, 9
	s_cbranch_scc1 .Llrufix_issued
	global_load_dwordx2 v[80:81], v56, s[8:9] offset:512
	s_cmp_le_u32 s22, 10
	s_cbranch_scc1 .Llrufix_issued
	global_load_dwordx2 v[82:83], v56, s[8:9] offset:1024
	s_cmp_le_u32 s22, 11
	s_cbranch_scc1 .Llrufix_issued
	global_load_dwordx2 v[84:85], v56, s[8:9] offset:1536
	s_cmp_le_u32 s22, 12
	s_cbranch_scc1 .Llrufix_issued
	global_load_dwordx2 v[86:87], v56, s[8:9] offset:2048
	s_cmp_le_u32 s22, 13
	s_cbranch_scc1 .Llrufix_issued
	global_load_dwordx2 v[88:89], v56, s[8:9] offset:2560
	s_cmp_le_u32 s22, 14
	s_cbranch_scc1 .Llrufix_issued
	global_load_dwordx2 v[90:91], v56, s[8:9] offset:3072
